# grid barrier: all workgroups poll the top-level generation word (one release hop less); leader L2 invalidate moved before its top-level arrival
# speedup vs baseline: 1.0336x; 1.0035x over previous
.LBB0_30:
	s_or_b64 exec, exec, s[10:11]
	v_cvt_f32_u32_e32 v5, v3
	s_waitcnt vmcnt(0)
	v_readfirstlane_b32 s7, v4
	v_sub_u32_e32 v4, 0, v3
	v_rcp_iflag_f32_e32 v5, v5
	v_add_u32_e32 v6, s7, v2
	v_mul_f32_e32 v5, 0x4f7ffffe, v5
	v_cvt_u32_f32_e32 v5, v5
	v_mul_lo_u32 v2, v4, v5
	v_mul_hi_u32 v2, v5, v2
	v_add_u32_e32 v2, v5, v2
	v_mul_hi_u32 v2, v6, v2
	v_mul_lo_u32 v4, v2, v3
	v_sub_u32_e32 v4, v6, v4
	v_add_u32_e32 v5, 1, v2
	v_cmp_ge_u32_e32 vcc, v4, v3
	s_nop 1
	v_cndmask_b32_e32 v2, v2, v5, vcc
	v_sub_u32_e32 v5, v4, v3
	v_cndmask_b32_e32 v4, v4, v5, vcc
	v_add_u32_e32 v5, 1, v2
	v_cmp_ge_u32_e32 vcc, v4, v3
	v_add_u32_e32 v4, 1, v6
	s_nop 0
	v_cndmask_b32_e32 v2, v2, v5, vcc
	v_mul_lo_u32 v5, v3, v2
	v_add_u32_e32 v3, v5, v3
	v_cmp_ne_u32_e32 vcc, v4, v3
	s_and_saveexec_b64 s[8:9], vcc
	s_xor_b64 s[8:9], exec, s[8:9]
	s_cbranch_execz .LBB0_44
	s_waitcnt lgkmcnt(0)
	v_mov_b32_e32 v1, 0x7000
	buffer_inv sc1
	global_load_dword v1, v1, s[82:83] offset:1280 sc1
	s_add_u32 s14, s82, 0x7500
	s_addc_u32 s15, s83, 0
	s_waitcnt vmcnt(0)
	v_cmp_eq_u32_e32 vcc, v1, v2
	s_and_saveexec_b64 s[10:11], vcc
	s_cbranch_execz .LBB0_43
	s_add_u32 s12, s82, 0x4200
	s_addc_u32 s13, s83, 0
	s_mov_b32 s7, 1
	s_mov_b64 s[16:17], 0
	v_mov_b32_e32 v1, 0
	s_branch .LBB0_34

.LBB0_44:
	s_andn2_saveexec_b64 s[8:9], s[8:9]
	s_cbranch_execz .LBB0_64
	s_mov_b64 s[8:9], exec
	buffer_wbl2 sc1
	buffer_inv sc1
	s_waitcnt lgkmcnt(0)
	s_waitcnt vmcnt(0)
	v_mbcnt_lo_u32_b32 v2, s8, 0
	v_mbcnt_hi_u32_b32 v2, s9, v2
	v_cmp_eq_u32_e32 vcc, 0, v2
	s_and_saveexec_b64 s[10:11], vcc
	s_cbranch_execz .LBB0_47
	s_bcnt1_i32_b64 s7, s[8:9]
	v_mov_b32_e32 v3, 0x7000
	v_mov_b32_e32 v4, s7
	global_atomic_add v3, v3, v4, s[82:83] offset:1024 sc0

.LBB0_137:
	s_or_b64 exec, exec, s[6:7]
	v_cvt_f32_u32_e32 v6, v4
	s_waitcnt vmcnt(0)
	v_readfirstlane_b32 s4, v5
	v_sub_u32_e32 v5, 0, v4
	v_rcp_iflag_f32_e32 v6, v6
	v_add_u32_e32 v7, s4, v3
	v_mul_f32_e32 v6, 0x4f7ffffe, v6
	v_cvt_u32_f32_e32 v6, v6
	v_mul_lo_u32 v3, v5, v6
	v_mul_hi_u32 v3, v6, v3
	v_add_u32_e32 v3, v6, v3
	v_mul_hi_u32 v3, v7, v3
	v_mul_lo_u32 v5, v3, v4
	v_sub_u32_e32 v5, v7, v5
	v_add_u32_e32 v6, 1, v3
	v_cmp_ge_u32_e32 vcc, v5, v4
	s_nop 1
	v_cndmask_b32_e32 v3, v3, v6, vcc
	v_sub_u32_e32 v6, v5, v4
	v_cndmask_b32_e32 v5, v5, v6, vcc
	v_add_u32_e32 v6, 1, v3
	v_cmp_ge_u32_e32 vcc, v5, v4
	v_add_u32_e32 v5, 1, v7
	s_nop 0
	v_cndmask_b32_e32 v3, v3, v6, vcc
	v_mul_lo_u32 v6, v4, v3
	v_add_u32_e32 v4, v6, v4
	v_cmp_ne_u32_e32 vcc, v5, v4
	s_and_saveexec_b64 s[4:5], vcc
	s_xor_b64 s[4:5], exec, s[4:5]
	s_cbranch_execz .LBB0_151
	s_waitcnt lgkmcnt(0)
	v_mov_b32_e32 v2, 0x7000
	buffer_inv sc1
	global_load_dword v2, v2, s[82:83] offset:1280 sc1
	s_add_u32 s10, s82, 0x7500
	s_addc_u32 s11, s83, 0
	s_waitcnt vmcnt(0)
	v_cmp_eq_u32_e32 vcc, v2, v3
	s_and_saveexec_b64 s[6:7], vcc
	s_cbranch_execz .LBB0_150
	s_add_u32 s8, s82, 0x4200
	s_addc_u32 s9, s83, 0
	s_mov_b32 s22, 1
	s_mov_b64 s[12:13], 0
	v_mov_b32_e32 v2, 0
	s_branch .LBB0_141

.LBB0_151:
	s_andn2_saveexec_b64 s[4:5], s[4:5]
	s_cbranch_execz .LBB0_171
	s_mov_b64 s[4:5], exec
	buffer_wbl2 sc1
	buffer_inv sc1
	s_waitcnt lgkmcnt(0)
	s_waitcnt vmcnt(0)
	v_mbcnt_lo_u32_b32 v3, s4, 0
	v_mbcnt_hi_u32_b32 v3, s5, v3
	v_cmp_eq_u32_e32 vcc, 0, v3
	s_and_saveexec_b64 s[6:7], vcc
	s_cbranch_execz .LBB0_154
	s_bcnt1_i32_b64 s4, s[4:5]
	v_mov_b32_e32 v4, 0x7000
	v_mov_b32_e32 v5, s4
	global_atomic_add v4, v4, v5, s[82:83] offset:1024 sc0
